# cache policy: non-temporal hint on the single-use feature loads of the scan staging waves
# baseline (speedup 1.0000x reference)
; #define UFOR(v, n) _Pragma("unroll") for (int v = 0; v < (n); ++v)
; __device__ __forceinline__ int scan_row(int c, int s, int b, int dir) {
;   if (c < 8) { const int ps = c * 32 + s; return ML + b * CTX + (dir ? (CTX - 1 - ps) : ps); }
;   const int ps = (c - 8) * 32 + s; return b * TL + (dir ? (TL - 1 - ps) : ps);
; __device__ __forceinline__ void phase_scan(KP p) {
;     ...
;           if (c + 3 < NCH) {
;             UFOR(e, 2) {
;               const int q = pt + 128 * e, st = q >> 3, g8 = q & 7;
;               const size_t o = (size_t)scan_row(c + 3, st, b, dir) * RW + h * 64 + g8 * 8;
;               rq[e][0] = *(const uint4*)(fr_ + o); rq[e][1] = *(const uint4*)(fdw + o); rq[e][2] = *(const uint4*)(fkey + o);
;               rq[e][3] = *(const uint4*)(fkk + o); rq[e][4] = *(const uint4*)(fb + o); rq[e][5] = *(const uint4*)(fv + o);
;             }
.LBB0_764:
	s_cmpk_gt_i32 s18, 0x204
	s_cbranch_scc1 .LBB0_766
	s_lshl_b32 s19, s18, 5
	s_add_i32 s74, s19, 0xffffff60
	s_addk_i32 s19, 0x60
	s_cmp_lt_i32 s18, 5
	s_waitcnt vmcnt(10)
	v_mov_b32_e32 v0, s15
	s_cselect_b64 s[50:51], -1, 0
	s_waitcnt vmcnt(5)
	v_cndmask_b32_e64 v24, v0, v151, s[50:51]
	s_and_b64 s[50:51], s[50:51], exec
	s_cselect_b32 s19, s19, s74
	s_movk_i32 s50, 0x3fff
	s_cselect_b32 s74, 0xff, s50
	v_or_b32_e32 v0, s19, v125
	v_or_b32_e32 v25, s19, v131
	v_sub_u32_e32 v1, s74, v0
	v_sub_u32_e32 v26, s74, v25
	v_cndmask_b32_e64 v0, v1, v0, s[46:47]
	v_cndmask_b32_e64 v25, v26, v25, s[46:47]
	v_add_u32_e32 v0, v0, v24
	s_movk_i32 s75, 0x300
	v_add_u32_e32 v24, v25, v24
	v_mad_i64_i32 v[0:1], s[50:51], v0, s75, v[114:115]
	v_mad_i64_i32 v[24:25], s[50:51], v24, s75, v[114:115]
	v_lshlrev_b64 v[16:17], 1, v[0:1]
	s_waitcnt vmcnt(1)
	v_lshlrev_b64 v[40:41], 1, v[24:25]
	v_lshl_add_u64 v[0:1], s[54:55], 0, v[16:17]
	v_lshl_add_u64 v[2:3], s[64:65], 0, v[16:17]
	v_lshl_add_u64 v[8:9], s[62:63], 0, v[16:17]
	v_lshl_add_u64 v[12:13], s[56:57], 0, v[16:17]
	v_lshl_add_u64 v[18:19], s[66:67], 0, v[16:17]
	v_lshl_add_u64 v[20:21], s[58:59], 0, v[16:17]
	v_lshl_add_u64 v[24:25], s[54:55], 0, v[40:41]
	s_waitcnt vmcnt(0)
	v_lshl_add_u64 v[28:29], s[64:65], 0, v[40:41]
	v_lshl_add_u64 v[32:33], s[62:63], 0, v[40:41]
	v_lshl_add_u64 v[36:37], s[56:57], 0, v[40:41]
	v_lshl_add_u64 v[42:43], s[66:67], 0, v[40:41]
	v_lshl_add_u64 v[44:45], s[58:59], 0, v[40:41]
	global_load_dwordx4 v[4:7], v[0:1], off nt
	s_nop 0
	global_load_dwordx4 v[0:3], v[2:3], off nt
	s_nop 0
	global_load_dwordx4 v[8:11], v[8:9], off nt
	s_nop 0
	global_load_dwordx4 v[12:15], v[12:13], off nt
	s_nop 0
	global_load_dwordx4 v[16:19], v[18:19], off nt
	s_nop 0
	global_load_dwordx4 v[20:23], v[20:21], off nt
	s_nop 0
	global_load_dwordx4 v[24:27], v[24:25], off nt
	s_nop 0
	global_load_dwordx4 v[28:31], v[28:29], off nt
	s_nop 0
	global_load_dwordx4 v[32:35], v[32:33], off nt
	s_nop 0
	global_load_dwordx4 v[36:39], v[36:37], off nt
	s_nop 0
	global_load_dwordx4 v[40:43], v[42:43], off nt
	s_nop 0
	global_load_dwordx4 v[44:47], v[44:45], off nt
